# gmlp_in UZ epilogue: packed f32 gelu*silu with a single reciprocal per element
# speedup vs baseline: 1.0132x; 1.0132x over previous
.LBB0_128:
	s_andn2_saveexec_b64 s[58:59], s[58:59]
	s_cbranch_execz .LBB0_113
	v_mov_b32_e32 v182, 0xc0135761
	v_mov_b32_e32 v183, 0xc0135761
	v_mov_b32_e32 v184, 0xbdd2d3e7
	v_mov_b32_e32 v185, 0xbdd2d3e7
	v_mov_b32_e32 v186, 0xbfb8aa3b
	v_mov_b32_e32 v187, 0xbfb8aa3b
	v_mov_b32_e32 v188, 0x3f800000
	v_mov_b32_e32 v189, 0x3f800000
	v_pk_mul_f32 v[190:191], v[124:125], v[124:125]
	v_pk_mul_f32 v[194:195], v[126:127], v[126:127]
	v_pk_fma_f32 v[190:191], v[190:191], v[184:185], v[182:183]
	v_pk_fma_f32 v[194:195], v[194:195], v[184:185], v[182:183]
	v_pk_mul_f32 v[190:191], v[124:125], v[190:191]
	v_pk_mul_f32 v[194:195], v[126:127], v[194:195]
	v_pk_mul_f32 v[192:193], v[120:121], v[186:187]
	v_pk_mul_f32 v[196:197], v[122:123], v[186:187]
	v_exp_f32_e32 v190, v190
	v_exp_f32_e32 v191, v191
	v_exp_f32_e32 v192, v192
	v_exp_f32_e32 v193, v193
	v_exp_f32_e32 v194, v194
	v_exp_f32_e32 v195, v195
	v_exp_f32_e32 v196, v196
	v_exp_f32_e32 v197, v197
	v_pk_add_f32 v[190:191], v[190:191], v[188:189]
	v_pk_add_f32 v[192:193], v[192:193], v[188:189]
	v_pk_add_f32 v[194:195], v[194:195], v[188:189]
	v_pk_add_f32 v[196:197], v[196:197], v[188:189]
	v_pk_mul_f32 v[190:191], v[190:191], v[192:193]
	v_pk_mul_f32 v[194:195], v[194:195], v[196:197]
	v_rcp_f32_e32 v190, v190
	v_rcp_f32_e32 v191, v191
	v_rcp_f32_e32 v194, v194
	v_rcp_f32_e32 v195, v195
	v_pk_mul_f32 v[192:193], v[124:125], v[120:121]
	v_pk_mul_f32 v[196:197], v[126:127], v[122:123]
	v_pk_mul_f32 v[190:191], v[192:193], v[190:191]
	v_pk_mul_f32 v[194:195], v[196:197], v[194:195]
	v_cvt_pk_bf16_f32 v200, v190, v191
	v_cvt_pk_bf16_f32 v201, v194, v195
	ds_write_b16 v150, v200
	ds_write_b16_d16_hi v150, v200 offset:144
	ds_write_b16 v150, v201 offset:288
	ds_write_b16_d16_hi v150, v201 offset:432
	v_pk_mul_f32 v[190:191], v[116:117], v[116:117]
	v_pk_mul_f32 v[194:195], v[118:119], v[118:119]
	v_pk_fma_f32 v[190:191], v[190:191], v[184:185], v[182:183]
	v_pk_fma_f32 v[194:195], v[194:195], v[184:185], v[182:183]
	v_pk_mul_f32 v[190:191], v[116:117], v[190:191]
	v_pk_mul_f32 v[194:195], v[118:119], v[194:195]
	v_pk_mul_f32 v[192:193], v[112:113], v[186:187]
	v_pk_mul_f32 v[196:197], v[114:115], v[186:187]
	v_exp_f32_e32 v190, v190
	v_exp_f32_e32 v191, v191
	v_exp_f32_e32 v192, v192
	v_exp_f32_e32 v193, v193
	v_exp_f32_e32 v194, v194
	v_exp_f32_e32 v195, v195
	v_exp_f32_e32 v196, v196
	v_exp_f32_e32 v197, v197
	v_pk_add_f32 v[190:191], v[190:191], v[188:189]
	v_pk_add_f32 v[192:193], v[192:193], v[188:189]
	v_pk_add_f32 v[194:195], v[194:195], v[188:189]
	v_pk_add_f32 v[196:197], v[196:197], v[188:189]
	v_pk_mul_f32 v[190:191], v[190:191], v[192:193]
	v_pk_mul_f32 v[194:195], v[194:195], v[196:197]
	v_rcp_f32_e32 v190, v190
	v_rcp_f32_e32 v191, v191
	v_rcp_f32_e32 v194, v194
	v_rcp_f32_e32 v195, v195
	v_pk_mul_f32 v[192:193], v[116:117], v[112:113]
	v_pk_mul_f32 v[196:197], v[118:119], v[114:115]
	v_pk_mul_f32 v[190:191], v[192:193], v[190:191]
	v_pk_mul_f32 v[194:195], v[196:197], v[194:195]
	v_cvt_pk_bf16_f32 v200, v190, v191
	v_cvt_pk_bf16_f32 v201, v194, v195
	ds_write_b16 v150, v200 offset:32
	ds_write_b16_d16_hi v150, v200 offset:176
	ds_write_b16 v150, v201 offset:320
	ds_write_b16_d16_hi v150, v201 offset:464
	v_pk_mul_f32 v[190:191], v[108:109], v[108:109]
	v_pk_mul_f32 v[194:195], v[110:111], v[110:111]
	v_pk_fma_f32 v[190:191], v[190:191], v[184:185], v[182:183]
	v_pk_fma_f32 v[194:195], v[194:195], v[184:185], v[182:183]
	v_pk_mul_f32 v[190:191], v[108:109], v[190:191]
	v_pk_mul_f32 v[194:195], v[110:111], v[194:195]
	v_pk_mul_f32 v[192:193], v[104:105], v[186:187]
	v_pk_mul_f32 v[196:197], v[106:107], v[186:187]
	v_exp_f32_e32 v190, v190
	v_exp_f32_e32 v191, v191
	v_exp_f32_e32 v192, v192
	v_exp_f32_e32 v193, v193
	v_exp_f32_e32 v194, v194
	v_exp_f32_e32 v195, v195
	v_exp_f32_e32 v196, v196
	v_exp_f32_e32 v197, v197
	v_pk_add_f32 v[190:191], v[190:191], v[188:189]
	v_pk_add_f32 v[192:193], v[192:193], v[188:189]
	v_pk_add_f32 v[194:195], v[194:195], v[188:189]
	v_pk_add_f32 v[196:197], v[196:197], v[188:189]
	v_pk_mul_f32 v[190:191], v[190:191], v[192:193]
	v_pk_mul_f32 v[194:195], v[194:195], v[196:197]
	v_rcp_f32_e32 v190, v190
	v_rcp_f32_e32 v191, v191
	v_rcp_f32_e32 v194, v194
	v_rcp_f32_e32 v195, v195
	v_pk_mul_f32 v[192:193], v[108:109], v[104:105]
	v_pk_mul_f32 v[196:197], v[110:111], v[106:107]
	v_pk_mul_f32 v[190:191], v[192:193], v[190:191]
	v_pk_mul_f32 v[194:195], v[196:197], v[194:195]
	v_cvt_pk_bf16_f32 v200, v190, v191
	v_cvt_pk_bf16_f32 v201, v194, v195
	ds_write_b16 v150, v200 offset:2304
	ds_write_b16_d16_hi v150, v200 offset:2448
	ds_write_b16 v150, v201 offset:2592
	ds_write_b16_d16_hi v150, v201 offset:2736
	v_pk_mul_f32 v[190:191], v[100:101], v[100:101]
	v_pk_mul_f32 v[194:195], v[102:103], v[102:103]
	v_pk_fma_f32 v[190:191], v[190:191], v[184:185], v[182:183]
	v_pk_fma_f32 v[194:195], v[194:195], v[184:185], v[182:183]
	v_pk_mul_f32 v[190:191], v[100:101], v[190:191]
	v_pk_mul_f32 v[194:195], v[102:103], v[194:195]
	v_pk_mul_f32 v[192:193], v[96:97], v[186:187]
	v_pk_mul_f32 v[196:197], v[98:99], v[186:187]
	v_exp_f32_e32 v190, v190
	v_exp_f32_e32 v191, v191
	v_exp_f32_e32 v192, v192
	v_exp_f32_e32 v193, v193
	v_exp_f32_e32 v194, v194
	v_exp_f32_e32 v195, v195
	v_exp_f32_e32 v196, v196
	v_exp_f32_e32 v197, v197
	v_pk_add_f32 v[190:191], v[190:191], v[188:189]
	v_pk_add_f32 v[192:193], v[192:193], v[188:189]
	v_pk_add_f32 v[194:195], v[194:195], v[188:189]
	v_pk_add_f32 v[196:197], v[196:197], v[188:189]
	v_pk_mul_f32 v[190:191], v[190:191], v[192:193]
	v_pk_mul_f32 v[194:195], v[194:195], v[196:197]
	v_rcp_f32_e32 v190, v190
	v_rcp_f32_e32 v191, v191
	v_rcp_f32_e32 v194, v194
	v_rcp_f32_e32 v195, v195
	v_pk_mul_f32 v[192:193], v[100:101], v[96:97]
	v_pk_mul_f32 v[196:197], v[102:103], v[98:99]
	v_pk_mul_f32 v[190:191], v[192:193], v[190:191]
	v_pk_mul_f32 v[194:195], v[196:197], v[194:195]
	v_cvt_pk_bf16_f32 v200, v190, v191
	v_cvt_pk_bf16_f32 v201, v194, v195
	ds_write_b16 v150, v200 offset:2336
	ds_write_b16_d16_hi v150, v200 offset:2480
	ds_write_b16 v150, v201 offset:2624
	ds_write_b16_d16_hi v150, v201 offset:2768
	v_pk_mul_f32 v[190:191], v[92:93], v[92:93]
	v_pk_mul_f32 v[194:195], v[94:95], v[94:95]
	v_pk_fma_f32 v[190:191], v[190:191], v[184:185], v[182:183]
	v_pk_fma_f32 v[194:195], v[194:195], v[184:185], v[182:183]
	v_pk_mul_f32 v[190:191], v[92:93], v[190:191]
	v_pk_mul_f32 v[194:195], v[94:95], v[194:195]
	v_pk_mul_f32 v[192:193], v[88:89], v[186:187]
	v_pk_mul_f32 v[196:197], v[90:91], v[186:187]
	v_exp_f32_e32 v190, v190
	v_exp_f32_e32 v191, v191
	v_exp_f32_e32 v192, v192
	v_exp_f32_e32 v193, v193
	v_exp_f32_e32 v194, v194
	v_exp_f32_e32 v195, v195
	v_exp_f32_e32 v196, v196
	v_exp_f32_e32 v197, v197
	v_pk_add_f32 v[190:191], v[190:191], v[188:189]
	v_pk_add_f32 v[192:193], v[192:193], v[188:189]
	v_pk_add_f32 v[194:195], v[194:195], v[188:189]
	v_pk_add_f32 v[196:197], v[196:197], v[188:189]
	v_pk_mul_f32 v[190:191], v[190:191], v[192:193]
	v_pk_mul_f32 v[194:195], v[194:195], v[196:197]
	v_rcp_f32_e32 v190, v190
	v_rcp_f32_e32 v191, v191
	v_rcp_f32_e32 v194, v194
	v_rcp_f32_e32 v195, v195
	v_pk_mul_f32 v[192:193], v[92:93], v[88:89]
	v_pk_mul_f32 v[196:197], v[94:95], v[90:91]
	v_pk_mul_f32 v[190:191], v[192:193], v[190:191]
	v_pk_mul_f32 v[194:195], v[196:197], v[194:195]
	v_cvt_pk_bf16_f32 v200, v190, v191
	v_cvt_pk_bf16_f32 v201, v194, v195
	ds_write_b16 v150, v200 offset:4608
	ds_write_b16_d16_hi v150, v200 offset:4752
	ds_write_b16 v150, v201 offset:4896
	ds_write_b16_d16_hi v150, v201 offset:5040
	v_pk_mul_f32 v[190:191], v[84:85], v[84:85]
	v_pk_mul_f32 v[194:195], v[86:87], v[86:87]
	v_pk_fma_f32 v[190:191], v[190:191], v[184:185], v[182:183]
	v_pk_fma_f32 v[194:195], v[194:195], v[184:185], v[182:183]
	v_pk_mul_f32 v[190:191], v[84:85], v[190:191]
	v_pk_mul_f32 v[194:195], v[86:87], v[194:195]
	v_pk_mul_f32 v[192:193], v[80:81], v[186:187]
	v_pk_mul_f32 v[196:197], v[82:83], v[186:187]
	v_exp_f32_e32 v190, v190
	v_exp_f32_e32 v191, v191
	v_exp_f32_e32 v192, v192
	v_exp_f32_e32 v193, v193
	v_exp_f32_e32 v194, v194
	v_exp_f32_e32 v195, v195
	v_exp_f32_e32 v196, v196
	v_exp_f32_e32 v197, v197
	v_pk_add_f32 v[190:191], v[190:191], v[188:189]
	v_pk_add_f32 v[192:193], v[192:193], v[188:189]
	v_pk_add_f32 v[194:195], v[194:195], v[188:189]
	v_pk_add_f32 v[196:197], v[196:197], v[188:189]
	v_pk_mul_f32 v[190:191], v[190:191], v[192:193]
	v_pk_mul_f32 v[194:195], v[194:195], v[196:197]
	v_rcp_f32_e32 v190, v190
	v_rcp_f32_e32 v191, v191
	v_rcp_f32_e32 v194, v194
	v_rcp_f32_e32 v195, v195
	v_pk_mul_f32 v[192:193], v[84:85], v[80:81]
	v_pk_mul_f32 v[196:197], v[86:87], v[82:83]
	v_pk_mul_f32 v[190:191], v[192:193], v[190:191]
	v_pk_mul_f32 v[194:195], v[196:197], v[194:195]
	v_cvt_pk_bf16_f32 v200, v190, v191
	v_cvt_pk_bf16_f32 v201, v194, v195
	ds_write_b16 v150, v200 offset:4640
	ds_write_b16_d16_hi v150, v200 offset:4784
	ds_write_b16 v150, v201 offset:4928
	ds_write_b16_d16_hi v150, v201 offset:5072
	v_pk_mul_f32 v[190:191], v[76:77], v[76:77]
	v_pk_mul_f32 v[194:195], v[78:79], v[78:79]
	v_pk_fma_f32 v[190:191], v[190:191], v[184:185], v[182:183]
	v_pk_fma_f32 v[194:195], v[194:195], v[184:185], v[182:183]
	v_pk_mul_f32 v[190:191], v[76:77], v[190:191]
	v_pk_mul_f32 v[194:195], v[78:79], v[194:195]
	v_pk_mul_f32 v[192:193], v[72:73], v[186:187]
	v_pk_mul_f32 v[196:197], v[74:75], v[186:187]
	v_exp_f32_e32 v190, v190
	v_exp_f32_e32 v191, v191
	v_exp_f32_e32 v192, v192
	v_exp_f32_e32 v193, v193
	v_exp_f32_e32 v194, v194
	v_exp_f32_e32 v195, v195
	v_exp_f32_e32 v196, v196
	v_exp_f32_e32 v197, v197
	v_pk_add_f32 v[190:191], v[190:191], v[188:189]
	v_pk_add_f32 v[192:193], v[192:193], v[188:189]
	v_pk_add_f32 v[194:195], v[194:195], v[188:189]
	v_pk_add_f32 v[196:197], v[196:197], v[188:189]
	v_pk_mul_f32 v[190:191], v[190:191], v[192:193]
	v_pk_mul_f32 v[194:195], v[194:195], v[196:197]
	v_rcp_f32_e32 v190, v190
	v_rcp_f32_e32 v191, v191
	v_rcp_f32_e32 v194, v194
	v_rcp_f32_e32 v195, v195
	v_pk_mul_f32 v[192:193], v[76:77], v[72:73]
	v_pk_mul_f32 v[196:197], v[78:79], v[74:75]
	v_pk_mul_f32 v[190:191], v[192:193], v[190:191]
	v_pk_mul_f32 v[194:195], v[196:197], v[194:195]
	v_cvt_pk_bf16_f32 v200, v190, v191
	v_cvt_pk_bf16_f32 v201, v194, v195
	ds_write_b16 v150, v200 offset:6912
	ds_write_b16_d16_hi v150, v200 offset:7056
	ds_write_b16 v150, v201 offset:7200
	ds_write_b16_d16_hi v150, v201 offset:7344
	v_pk_mul_f32 v[190:191], v[68:69], v[68:69]
	v_pk_mul_f32 v[194:195], v[70:71], v[70:71]
	v_pk_fma_f32 v[190:191], v[190:191], v[184:185], v[182:183]
	v_pk_fma_f32 v[194:195], v[194:195], v[184:185], v[182:183]
	v_pk_mul_f32 v[190:191], v[68:69], v[190:191]
	v_pk_mul_f32 v[194:195], v[70:71], v[194:195]
	v_pk_mul_f32 v[192:193], v[64:65], v[186:187]
	v_pk_mul_f32 v[196:197], v[66:67], v[186:187]
	v_exp_f32_e32 v190, v190
	v_exp_f32_e32 v191, v191
	v_exp_f32_e32 v192, v192
	v_exp_f32_e32 v193, v193
	v_exp_f32_e32 v194, v194
	v_exp_f32_e32 v195, v195
	v_exp_f32_e32 v196, v196
	v_exp_f32_e32 v197, v197
	v_pk_add_f32 v[190:191], v[190:191], v[188:189]
	v_pk_add_f32 v[192:193], v[192:193], v[188:189]
	v_pk_add_f32 v[194:195], v[194:195], v[188:189]
	v_pk_add_f32 v[196:197], v[196:197], v[188:189]
	v_pk_mul_f32 v[190:191], v[190:191], v[192:193]
	v_pk_mul_f32 v[194:195], v[194:195], v[196:197]
	v_rcp_f32_e32 v190, v190
	v_rcp_f32_e32 v191, v191
	v_rcp_f32_e32 v194, v194
	v_rcp_f32_e32 v195, v195
	v_pk_mul_f32 v[192:193], v[68:69], v[64:65]
	v_pk_mul_f32 v[196:197], v[70:71], v[66:67]
	v_pk_mul_f32 v[190:191], v[192:193], v[190:191]
	v_pk_mul_f32 v[194:195], v[196:197], v[194:195]
	v_cvt_pk_bf16_f32 v200, v190, v191
	v_cvt_pk_bf16_f32 v201, v194, v195
	ds_write_b16 v150, v200 offset:6944
	ds_write_b16_d16_hi v150, v200 offset:7088
	ds_write_b16 v150, v201 offset:7232
	ds_write_b16_d16_hi v150, v201 offset:7376
	v_pk_mul_f32 v[190:191], v[60:61], v[60:61]
	v_pk_mul_f32 v[194:195], v[62:63], v[62:63]
	v_pk_fma_f32 v[190:191], v[190:191], v[184:185], v[182:183]
	v_pk_fma_f32 v[194:195], v[194:195], v[184:185], v[182:183]
	v_pk_mul_f32 v[190:191], v[60:61], v[190:191]
	v_pk_mul_f32 v[194:195], v[62:63], v[194:195]
	v_pk_mul_f32 v[192:193], v[56:57], v[186:187]
	v_pk_mul_f32 v[196:197], v[58:59], v[186:187]
	v_exp_f32_e32 v190, v190
	v_exp_f32_e32 v191, v191
	v_exp_f32_e32 v192, v192
	v_exp_f32_e32 v193, v193
	v_exp_f32_e32 v194, v194
	v_exp_f32_e32 v195, v195
	v_exp_f32_e32 v196, v196
	v_exp_f32_e32 v197, v197
	v_pk_add_f32 v[190:191], v[190:191], v[188:189]
	v_pk_add_f32 v[192:193], v[192:193], v[188:189]
	v_pk_add_f32 v[194:195], v[194:195], v[188:189]
	v_pk_add_f32 v[196:197], v[196:197], v[188:189]
	v_pk_mul_f32 v[190:191], v[190:191], v[192:193]
	v_pk_mul_f32 v[194:195], v[194:195], v[196:197]
	v_rcp_f32_e32 v190, v190
	v_rcp_f32_e32 v191, v191
	v_rcp_f32_e32 v194, v194
	v_rcp_f32_e32 v195, v195
	v_pk_mul_f32 v[192:193], v[60:61], v[56:57]
	v_pk_mul_f32 v[196:197], v[62:63], v[58:59]
	v_pk_mul_f32 v[190:191], v[192:193], v[190:191]
	v_pk_mul_f32 v[194:195], v[196:197], v[194:195]
	v_cvt_pk_bf16_f32 v200, v190, v191
	v_cvt_pk_bf16_f32 v201, v194, v195
	ds_write_b16 v150, v200 offset:9216
	ds_write_b16_d16_hi v150, v200 offset:9360
	ds_write_b16 v150, v201 offset:9504
	ds_write_b16_d16_hi v150, v201 offset:9648
	v_pk_mul_f32 v[190:191], v[52:53], v[52:53]
	v_pk_mul_f32 v[194:195], v[54:55], v[54:55]
	v_pk_fma_f32 v[190:191], v[190:191], v[184:185], v[182:183]
	v_pk_fma_f32 v[194:195], v[194:195], v[184:185], v[182:183]
	v_pk_mul_f32 v[190:191], v[52:53], v[190:191]
	v_pk_mul_f32 v[194:195], v[54:55], v[194:195]
	v_pk_mul_f32 v[192:193], v[48:49], v[186:187]
	v_pk_mul_f32 v[196:197], v[50:51], v[186:187]
	v_exp_f32_e32 v190, v190
	v_exp_f32_e32 v191, v191
	v_exp_f32_e32 v192, v192
	v_exp_f32_e32 v193, v193
	v_exp_f32_e32 v194, v194
	v_exp_f32_e32 v195, v195
	v_exp_f32_e32 v196, v196
	v_exp_f32_e32 v197, v197
	v_pk_add_f32 v[190:191], v[190:191], v[188:189]
	v_pk_add_f32 v[192:193], v[192:193], v[188:189]
	v_pk_add_f32 v[194:195], v[194:195], v[188:189]
	v_pk_add_f32 v[196:197], v[196:197], v[188:189]
	v_pk_mul_f32 v[190:191], v[190:191], v[192:193]
	v_pk_mul_f32 v[194:195], v[194:195], v[196:197]
	v_rcp_f32_e32 v190, v190
	v_rcp_f32_e32 v191, v191
	v_rcp_f32_e32 v194, v194
	v_rcp_f32_e32 v195, v195
	v_pk_mul_f32 v[192:193], v[52:53], v[48:49]
	v_pk_mul_f32 v[196:197], v[54:55], v[50:51]
	v_pk_mul_f32 v[190:191], v[192:193], v[190:191]
	v_pk_mul_f32 v[194:195], v[196:197], v[194:195]
	v_cvt_pk_bf16_f32 v200, v190, v191
	v_cvt_pk_bf16_f32 v201, v194, v195
	ds_write_b16 v150, v200 offset:9248
	ds_write_b16_d16_hi v150, v200 offset:9392
	ds_write_b16 v150, v201 offset:9536
	ds_write_b16_d16_hi v150, v201 offset:9680
	v_pk_mul_f32 v[190:191], v[44:45], v[44:45]
	v_pk_mul_f32 v[194:195], v[46:47], v[46:47]
	v_pk_fma_f32 v[190:191], v[190:191], v[184:185], v[182:183]
	v_pk_fma_f32 v[194:195], v[194:195], v[184:185], v[182:183]
	v_pk_mul_f32 v[190:191], v[44:45], v[190:191]
	v_pk_mul_f32 v[194:195], v[46:47], v[194:195]
	v_pk_mul_f32 v[192:193], v[40:41], v[186:187]
	v_pk_mul_f32 v[196:197], v[42:43], v[186:187]
	v_exp_f32_e32 v190, v190
	v_exp_f32_e32 v191, v191
	v_exp_f32_e32 v192, v192
	v_exp_f32_e32 v193, v193
	v_exp_f32_e32 v194, v194
	v_exp_f32_e32 v195, v195
	v_exp_f32_e32 v196, v196
	v_exp_f32_e32 v197, v197
	v_pk_add_f32 v[190:191], v[190:191], v[188:189]
	v_pk_add_f32 v[192:193], v[192:193], v[188:189]
	v_pk_add_f32 v[194:195], v[194:195], v[188:189]
	v_pk_add_f32 v[196:197], v[196:197], v[188:189]
	v_pk_mul_f32 v[190:191], v[190:191], v[192:193]
	v_pk_mul_f32 v[194:195], v[194:195], v[196:197]
	v_rcp_f32_e32 v190, v190
	v_rcp_f32_e32 v191, v191
	v_rcp_f32_e32 v194, v194
	v_rcp_f32_e32 v195, v195
	v_pk_mul_f32 v[192:193], v[44:45], v[40:41]
	v_pk_mul_f32 v[196:197], v[46:47], v[42:43]
	v_pk_mul_f32 v[190:191], v[192:193], v[190:191]
	v_pk_mul_f32 v[194:195], v[196:197], v[194:195]
	v_cvt_pk_bf16_f32 v200, v190, v191
	v_cvt_pk_bf16_f32 v201, v194, v195
	ds_write_b16 v150, v200 offset:11520
	ds_write_b16_d16_hi v150, v200 offset:11664
	ds_write_b16 v150, v201 offset:11808
	ds_write_b16_d16_hi v150, v201 offset:11952
	v_pk_mul_f32 v[190:191], v[36:37], v[36:37]
	v_pk_mul_f32 v[194:195], v[38:39], v[38:39]
	v_pk_fma_f32 v[190:191], v[190:191], v[184:185], v[182:183]
	v_pk_fma_f32 v[194:195], v[194:195], v[184:185], v[182:183]
	v_pk_mul_f32 v[190:191], v[36:37], v[190:191]
	v_pk_mul_f32 v[194:195], v[38:39], v[194:195]
	v_pk_mul_f32 v[192:193], v[32:33], v[186:187]
	v_pk_mul_f32 v[196:197], v[34:35], v[186:187]
	v_exp_f32_e32 v190, v190
	v_exp_f32_e32 v191, v191
	v_exp_f32_e32 v192, v192
	v_exp_f32_e32 v193, v193
	v_exp_f32_e32 v194, v194
	v_exp_f32_e32 v195, v195
	v_exp_f32_e32 v196, v196
	v_exp_f32_e32 v197, v197
	v_pk_add_f32 v[190:191], v[190:191], v[188:189]
	v_pk_add_f32 v[192:193], v[192:193], v[188:189]
	v_pk_add_f32 v[194:195], v[194:195], v[188:189]
	v_pk_add_f32 v[196:197], v[196:197], v[188:189]
	v_pk_mul_f32 v[190:191], v[190:191], v[192:193]
	v_pk_mul_f32 v[194:195], v[194:195], v[196:197]
	v_rcp_f32_e32 v190, v190
	v_rcp_f32_e32 v191, v191
	v_rcp_f32_e32 v194, v194
	v_rcp_f32_e32 v195, v195
	v_pk_mul_f32 v[192:193], v[36:37], v[32:33]
	v_pk_mul_f32 v[196:197], v[38:39], v[34:35]
	v_pk_mul_f32 v[190:191], v[192:193], v[190:191]
	v_pk_mul_f32 v[194:195], v[196:197], v[194:195]
	v_cvt_pk_bf16_f32 v200, v190, v191
	v_cvt_pk_bf16_f32 v201, v194, v195
	ds_write_b16 v150, v200 offset:11552
	ds_write_b16_d16_hi v150, v200 offset:11696
	ds_write_b16 v150, v201 offset:11840
	ds_write_b16_d16_hi v150, v201 offset:11984
	v_pk_mul_f32 v[190:191], v[28:29], v[28:29]
	v_pk_mul_f32 v[194:195], v[30:31], v[30:31]
	v_pk_fma_f32 v[190:191], v[190:191], v[184:185], v[182:183]
	v_pk_fma_f32 v[194:195], v[194:195], v[184:185], v[182:183]
	v_pk_mul_f32 v[190:191], v[28:29], v[190:191]
	v_pk_mul_f32 v[194:195], v[30:31], v[194:195]
	v_pk_mul_f32 v[192:193], v[24:25], v[186:187]
	v_pk_mul_f32 v[196:197], v[26:27], v[186:187]
	v_exp_f32_e32 v190, v190
	v_exp_f32_e32 v191, v191
	v_exp_f32_e32 v192, v192
	v_exp_f32_e32 v193, v193
	v_exp_f32_e32 v194, v194
	v_exp_f32_e32 v195, v195
	v_exp_f32_e32 v196, v196
	v_exp_f32_e32 v197, v197
	v_pk_add_f32 v[190:191], v[190:191], v[188:189]
	v_pk_add_f32 v[192:193], v[192:193], v[188:189]
	v_pk_add_f32 v[194:195], v[194:195], v[188:189]
	v_pk_add_f32 v[196:197], v[196:197], v[188:189]
	v_pk_mul_f32 v[190:191], v[190:191], v[192:193]
	v_pk_mul_f32 v[194:195], v[194:195], v[196:197]
	v_rcp_f32_e32 v190, v190
	v_rcp_f32_e32 v191, v191
	v_rcp_f32_e32 v194, v194
	v_rcp_f32_e32 v195, v195
	v_pk_mul_f32 v[192:193], v[28:29], v[24:25]
	v_pk_mul_f32 v[196:197], v[30:31], v[26:27]
	v_pk_mul_f32 v[190:191], v[192:193], v[190:191]
	v_pk_mul_f32 v[194:195], v[196:197], v[194:195]
	v_cvt_pk_bf16_f32 v200, v190, v191
	v_cvt_pk_bf16_f32 v201, v194, v195
	ds_write_b16 v150, v200 offset:13824
	ds_write_b16_d16_hi v150, v200 offset:13968
	ds_write_b16 v150, v201 offset:14112
	ds_write_b16_d16_hi v150, v201 offset:14256
	v_pk_mul_f32 v[190:191], v[16:17], v[16:17]
	v_pk_mul_f32 v[194:195], v[18:19], v[18:19]
	v_pk_fma_f32 v[190:191], v[190:191], v[184:185], v[182:183]
	v_pk_fma_f32 v[194:195], v[194:195], v[184:185], v[182:183]
	v_pk_mul_f32 v[190:191], v[16:17], v[190:191]
	v_pk_mul_f32 v[194:195], v[18:19], v[194:195]
	v_pk_mul_f32 v[192:193], v[12:13], v[186:187]
	v_pk_mul_f32 v[196:197], v[14:15], v[186:187]
	v_exp_f32_e32 v190, v190
	v_exp_f32_e32 v191, v191
	v_exp_f32_e32 v192, v192
	v_exp_f32_e32 v193, v193
	v_exp_f32_e32 v194, v194
	v_exp_f32_e32 v195, v195
	v_exp_f32_e32 v196, v196
	v_exp_f32_e32 v197, v197
	v_pk_add_f32 v[190:191], v[190:191], v[188:189]
	v_pk_add_f32 v[192:193], v[192:193], v[188:189]
	v_pk_add_f32 v[194:195], v[194:195], v[188:189]
	v_pk_add_f32 v[196:197], v[196:197], v[188:189]
	v_pk_mul_f32 v[190:191], v[190:191], v[192:193]
	v_pk_mul_f32 v[194:195], v[194:195], v[196:197]
	v_rcp_f32_e32 v190, v190
	v_rcp_f32_e32 v191, v191
	v_rcp_f32_e32 v194, v194
	v_rcp_f32_e32 v195, v195
	v_pk_mul_f32 v[192:193], v[16:17], v[12:13]
	v_pk_mul_f32 v[196:197], v[18:19], v[14:15]
	v_pk_mul_f32 v[190:191], v[192:193], v[190:191]
	v_pk_mul_f32 v[194:195], v[196:197], v[194:195]
	v_cvt_pk_bf16_f32 v200, v190, v191
	v_cvt_pk_bf16_f32 v201, v194, v195
	ds_write_b16 v150, v200 offset:13856
	ds_write_b16_d16_hi v150, v200 offset:14000
	ds_write_b16 v150, v201 offset:14144
	ds_write_b16_d16_hi v150, v201 offset:14288
	v_pk_mul_f32 v[190:191], v[4:5], v[4:5]
	v_pk_mul_f32 v[194:195], v[6:7], v[6:7]
	v_pk_fma_f32 v[190:191], v[190:191], v[184:185], v[182:183]
	v_pk_fma_f32 v[194:195], v[194:195], v[184:185], v[182:183]
	v_pk_mul_f32 v[190:191], v[4:5], v[190:191]
	v_pk_mul_f32 v[194:195], v[6:7], v[194:195]
	v_pk_mul_f32 v[192:193], v[20:21], v[186:187]
	v_pk_mul_f32 v[196:197], v[22:23], v[186:187]
	v_exp_f32_e32 v190, v190
	v_exp_f32_e32 v191, v191
	v_exp_f32_e32 v192, v192
	v_exp_f32_e32 v193, v193
	v_exp_f32_e32 v194, v194
	v_exp_f32_e32 v195, v195
	v_exp_f32_e32 v196, v196
	v_exp_f32_e32 v197, v197
	v_pk_add_f32 v[190:191], v[190:191], v[188:189]
	v_pk_add_f32 v[192:193], v[192:193], v[188:189]
	v_pk_add_f32 v[194:195], v[194:195], v[188:189]
	v_pk_add_f32 v[196:197], v[196:197], v[188:189]
	v_pk_mul_f32 v[190:191], v[190:191], v[192:193]
	v_pk_mul_f32 v[194:195], v[194:195], v[196:197]
	v_rcp_f32_e32 v190, v190
	v_rcp_f32_e32 v191, v191
	v_rcp_f32_e32 v194, v194
	v_rcp_f32_e32 v195, v195
	v_pk_mul_f32 v[192:193], v[4:5], v[20:21]
	v_pk_mul_f32 v[196:197], v[6:7], v[22:23]
	v_pk_mul_f32 v[190:191], v[192:193], v[190:191]
	v_pk_mul_f32 v[194:195], v[196:197], v[194:195]
	v_cvt_pk_bf16_f32 v200, v190, v191
	v_cvt_pk_bf16_f32 v201, v194, v195
	ds_write_b16 v150, v200 offset:16128
	ds_write_b16_d16_hi v150, v200 offset:16272
	ds_write_b16 v150, v201 offset:16416
	ds_write_b16_d16_hi v150, v201 offset:16560
	v_pk_mul_f32 v[190:191], v[0:1], v[0:1]
	v_pk_mul_f32 v[194:195], v[2:3], v[2:3]
	v_pk_fma_f32 v[190:191], v[190:191], v[184:185], v[182:183]
	v_pk_fma_f32 v[194:195], v[194:195], v[184:185], v[182:183]
	v_pk_mul_f32 v[190:191], v[0:1], v[190:191]
	v_pk_mul_f32 v[194:195], v[2:3], v[194:195]
	v_pk_mul_f32 v[192:193], v[8:9], v[186:187]
	v_pk_mul_f32 v[196:197], v[10:11], v[186:187]
	v_exp_f32_e32 v190, v190
	v_exp_f32_e32 v191, v191
	v_exp_f32_e32 v192, v192
	v_exp_f32_e32 v193, v193
	v_exp_f32_e32 v194, v194
	v_exp_f32_e32 v195, v195
	v_exp_f32_e32 v196, v196
	v_exp_f32_e32 v197, v197
	v_pk_add_f32 v[190:191], v[190:191], v[188:189]
	v_pk_add_f32 v[192:193], v[192:193], v[188:189]
	v_pk_add_f32 v[194:195], v[194:195], v[188:189]
	v_pk_add_f32 v[196:197], v[196:197], v[188:189]
	v_pk_mul_f32 v[190:191], v[190:191], v[192:193]
	v_pk_mul_f32 v[194:195], v[194:195], v[196:197]
	v_rcp_f32_e32 v190, v190
	v_rcp_f32_e32 v191, v191
	v_rcp_f32_e32 v194, v194
	v_rcp_f32_e32 v195, v195
	v_pk_mul_f32 v[192:193], v[0:1], v[8:9]
	v_pk_mul_f32 v[196:197], v[2:3], v[10:11]
	v_pk_mul_f32 v[190:191], v[192:193], v[190:191]
	v_pk_mul_f32 v[194:195], v[196:197], v[194:195]
	v_cvt_pk_bf16_f32 v200, v190, v191
	v_cvt_pk_bf16_f32 v201, v194, v195
	ds_write_b16 v150, v200 offset:16160
	ds_write_b16_d16_hi v150, v200 offset:16304
	ds_write_b16 v150, v201 offset:16448
	ds_write_b16_d16_hi v150, v201 offset:16592
	s_lshl_b32 s20, s93, 2
	s_lshl_b32 s60, s94, 2
	s_and_b32 s20, s20, 0x7fffff0
	v_add_u32_e32 v134, s88, v149
	s_or_b32 s20, s60, s20
	v_ashrrev_i32_e32 v135, 31, v134
	v_lshlrev_b64 v[134:135], 12, v[134:135]
	s_mov_b64 s[60:61], 0
	v_add_lshl_u32 v0, s20, v147, 5
	s_waitcnt lgkmcnt(0)
	v_ashrrev_i32_e32 v1, 31, v0
	v_lshl_add_u64 v[0:1], v[0:1], 1, v[134:135]
	v_lshl_add_u64 v[0:1], v[132:133], 0, v[0:1]
	v_mov_b32_e32 v2, v153

.LBB0_1502:
	s_andn2_saveexec_b64 s[42:43], s[42:43]
	s_cbranch_execz .LBB0_1487
	v_mov_b32_e32 v182, 0xc0135761
	v_mov_b32_e32 v183, 0xc0135761
	v_mov_b32_e32 v184, 0xbdd2d3e7
	v_mov_b32_e32 v185, 0xbdd2d3e7
	v_mov_b32_e32 v186, 0xbfb8aa3b
	v_mov_b32_e32 v187, 0xbfb8aa3b
	v_mov_b32_e32 v188, 0x3f800000
	v_mov_b32_e32 v189, 0x3f800000
	v_pk_mul_f32 v[190:191], v[124:125], v[124:125]
	v_pk_mul_f32 v[194:195], v[126:127], v[126:127]
	v_pk_fma_f32 v[190:191], v[190:191], v[184:185], v[182:183]
	v_pk_fma_f32 v[194:195], v[194:195], v[184:185], v[182:183]
	v_pk_mul_f32 v[190:191], v[124:125], v[190:191]
	v_pk_mul_f32 v[194:195], v[126:127], v[194:195]
	v_pk_mul_f32 v[192:193], v[120:121], v[186:187]
	v_pk_mul_f32 v[196:197], v[122:123], v[186:187]
	v_exp_f32_e32 v190, v190
	v_exp_f32_e32 v191, v191
	v_exp_f32_e32 v192, v192
	v_exp_f32_e32 v193, v193
	v_exp_f32_e32 v194, v194
	v_exp_f32_e32 v195, v195
	v_exp_f32_e32 v196, v196
	v_exp_f32_e32 v197, v197
	v_pk_add_f32 v[190:191], v[190:191], v[188:189]
	v_pk_add_f32 v[192:193], v[192:193], v[188:189]
	v_pk_add_f32 v[194:195], v[194:195], v[188:189]
	v_pk_add_f32 v[196:197], v[196:197], v[188:189]
	v_pk_mul_f32 v[190:191], v[190:191], v[192:193]
	v_pk_mul_f32 v[194:195], v[194:195], v[196:197]
	v_rcp_f32_e32 v190, v190
	v_rcp_f32_e32 v191, v191
	v_rcp_f32_e32 v194, v194
	v_rcp_f32_e32 v195, v195
	v_pk_mul_f32 v[192:193], v[124:125], v[120:121]
	v_pk_mul_f32 v[196:197], v[126:127], v[122:123]
	v_pk_mul_f32 v[190:191], v[192:193], v[190:191]
	v_pk_mul_f32 v[194:195], v[196:197], v[194:195]
	v_cvt_pk_bf16_f32 v200, v190, v191
	v_cvt_pk_bf16_f32 v201, v194, v195
	ds_write_b16 v150, v200
	ds_write_b16_d16_hi v150, v200 offset:144
	ds_write_b16 v150, v201 offset:288
	ds_write_b16_d16_hi v150, v201 offset:432
	v_pk_mul_f32 v[190:191], v[116:117], v[116:117]
	v_pk_mul_f32 v[194:195], v[118:119], v[118:119]
	v_pk_fma_f32 v[190:191], v[190:191], v[184:185], v[182:183]
	v_pk_fma_f32 v[194:195], v[194:195], v[184:185], v[182:183]
	v_pk_mul_f32 v[190:191], v[116:117], v[190:191]
	v_pk_mul_f32 v[194:195], v[118:119], v[194:195]
	v_pk_mul_f32 v[192:193], v[112:113], v[186:187]
	v_pk_mul_f32 v[196:197], v[114:115], v[186:187]
	v_exp_f32_e32 v190, v190
	v_exp_f32_e32 v191, v191
	v_exp_f32_e32 v192, v192
	v_exp_f32_e32 v193, v193
	v_exp_f32_e32 v194, v194
	v_exp_f32_e32 v195, v195
	v_exp_f32_e32 v196, v196
	v_exp_f32_e32 v197, v197
	v_pk_add_f32 v[190:191], v[190:191], v[188:189]
	v_pk_add_f32 v[192:193], v[192:193], v[188:189]
	v_pk_add_f32 v[194:195], v[194:195], v[188:189]
	v_pk_add_f32 v[196:197], v[196:197], v[188:189]
	v_pk_mul_f32 v[190:191], v[190:191], v[192:193]
	v_pk_mul_f32 v[194:195], v[194:195], v[196:197]
	v_rcp_f32_e32 v190, v190
	v_rcp_f32_e32 v191, v191
	v_rcp_f32_e32 v194, v194
	v_rcp_f32_e32 v195, v195
	v_pk_mul_f32 v[192:193], v[116:117], v[112:113]
	v_pk_mul_f32 v[196:197], v[118:119], v[114:115]
	v_pk_mul_f32 v[190:191], v[192:193], v[190:191]
	v_pk_mul_f32 v[194:195], v[196:197], v[194:195]
	v_cvt_pk_bf16_f32 v200, v190, v191
	v_cvt_pk_bf16_f32 v201, v194, v195
	ds_write_b16 v150, v200 offset:32
	ds_write_b16_d16_hi v150, v200 offset:176
	ds_write_b16 v150, v201 offset:320
	ds_write_b16_d16_hi v150, v201 offset:464
	v_pk_mul_f32 v[190:191], v[108:109], v[108:109]
	v_pk_mul_f32 v[194:195], v[110:111], v[110:111]
	v_pk_fma_f32 v[190:191], v[190:191], v[184:185], v[182:183]
	v_pk_fma_f32 v[194:195], v[194:195], v[184:185], v[182:183]
	v_pk_mul_f32 v[190:191], v[108:109], v[190:191]
	v_pk_mul_f32 v[194:195], v[110:111], v[194:195]
	v_pk_mul_f32 v[192:193], v[104:105], v[186:187]
	v_pk_mul_f32 v[196:197], v[106:107], v[186:187]
	v_exp_f32_e32 v190, v190
	v_exp_f32_e32 v191, v191
	v_exp_f32_e32 v192, v192
	v_exp_f32_e32 v193, v193
	v_exp_f32_e32 v194, v194
	v_exp_f32_e32 v195, v195
	v_exp_f32_e32 v196, v196
	v_exp_f32_e32 v197, v197
	v_pk_add_f32 v[190:191], v[190:191], v[188:189]
	v_pk_add_f32 v[192:193], v[192:193], v[188:189]
	v_pk_add_f32 v[194:195], v[194:195], v[188:189]
	v_pk_add_f32 v[196:197], v[196:197], v[188:189]
	v_pk_mul_f32 v[190:191], v[190:191], v[192:193]
	v_pk_mul_f32 v[194:195], v[194:195], v[196:197]
	v_rcp_f32_e32 v190, v190
	v_rcp_f32_e32 v191, v191
	v_rcp_f32_e32 v194, v194
	v_rcp_f32_e32 v195, v195
	v_pk_mul_f32 v[192:193], v[108:109], v[104:105]
	v_pk_mul_f32 v[196:197], v[110:111], v[106:107]
	v_pk_mul_f32 v[190:191], v[192:193], v[190:191]
	v_pk_mul_f32 v[194:195], v[196:197], v[194:195]
	v_cvt_pk_bf16_f32 v200, v190, v191
	v_cvt_pk_bf16_f32 v201, v194, v195
	ds_write_b16 v150, v200 offset:2304
	ds_write_b16_d16_hi v150, v200 offset:2448
	ds_write_b16 v150, v201 offset:2592
	ds_write_b16_d16_hi v150, v201 offset:2736
	v_pk_mul_f32 v[190:191], v[100:101], v[100:101]
	v_pk_mul_f32 v[194:195], v[102:103], v[102:103]
	v_pk_fma_f32 v[190:191], v[190:191], v[184:185], v[182:183]
	v_pk_fma_f32 v[194:195], v[194:195], v[184:185], v[182:183]
	v_pk_mul_f32 v[190:191], v[100:101], v[190:191]
	v_pk_mul_f32 v[194:195], v[102:103], v[194:195]
	v_pk_mul_f32 v[192:193], v[96:97], v[186:187]
	v_pk_mul_f32 v[196:197], v[98:99], v[186:187]
	v_exp_f32_e32 v190, v190
	v_exp_f32_e32 v191, v191
	v_exp_f32_e32 v192, v192
	v_exp_f32_e32 v193, v193
	v_exp_f32_e32 v194, v194
	v_exp_f32_e32 v195, v195
	v_exp_f32_e32 v196, v196
	v_exp_f32_e32 v197, v197
	v_pk_add_f32 v[190:191], v[190:191], v[188:189]
	v_pk_add_f32 v[192:193], v[192:193], v[188:189]
	v_pk_add_f32 v[194:195], v[194:195], v[188:189]
	v_pk_add_f32 v[196:197], v[196:197], v[188:189]
	v_pk_mul_f32 v[190:191], v[190:191], v[192:193]
	v_pk_mul_f32 v[194:195], v[194:195], v[196:197]
	v_rcp_f32_e32 v190, v190
	v_rcp_f32_e32 v191, v191
	v_rcp_f32_e32 v194, v194
	v_rcp_f32_e32 v195, v195
	v_pk_mul_f32 v[192:193], v[100:101], v[96:97]
	v_pk_mul_f32 v[196:197], v[102:103], v[98:99]
	v_pk_mul_f32 v[190:191], v[192:193], v[190:191]
	v_pk_mul_f32 v[194:195], v[196:197], v[194:195]
	v_cvt_pk_bf16_f32 v200, v190, v191
	v_cvt_pk_bf16_f32 v201, v194, v195
	ds_write_b16 v150, v200 offset:2336
	ds_write_b16_d16_hi v150, v200 offset:2480
	ds_write_b16 v150, v201 offset:2624
	ds_write_b16_d16_hi v150, v201 offset:2768
	v_pk_mul_f32 v[190:191], v[92:93], v[92:93]
	v_pk_mul_f32 v[194:195], v[94:95], v[94:95]
	v_pk_fma_f32 v[190:191], v[190:191], v[184:185], v[182:183]
	v_pk_fma_f32 v[194:195], v[194:195], v[184:185], v[182:183]
	v_pk_mul_f32 v[190:191], v[92:93], v[190:191]
	v_pk_mul_f32 v[194:195], v[94:95], v[194:195]
	v_pk_mul_f32 v[192:193], v[88:89], v[186:187]
	v_pk_mul_f32 v[196:197], v[90:91], v[186:187]
	v_exp_f32_e32 v190, v190
	v_exp_f32_e32 v191, v191
	v_exp_f32_e32 v192, v192
	v_exp_f32_e32 v193, v193
	v_exp_f32_e32 v194, v194
	v_exp_f32_e32 v195, v195
	v_exp_f32_e32 v196, v196
	v_exp_f32_e32 v197, v197
	v_pk_add_f32 v[190:191], v[190:191], v[188:189]
	v_pk_add_f32 v[192:193], v[192:193], v[188:189]
	v_pk_add_f32 v[194:195], v[194:195], v[188:189]
	v_pk_add_f32 v[196:197], v[196:197], v[188:189]
	v_pk_mul_f32 v[190:191], v[190:191], v[192:193]
	v_pk_mul_f32 v[194:195], v[194:195], v[196:197]
	v_rcp_f32_e32 v190, v190
	v_rcp_f32_e32 v191, v191
	v_rcp_f32_e32 v194, v194
	v_rcp_f32_e32 v195, v195
	v_pk_mul_f32 v[192:193], v[92:93], v[88:89]
	v_pk_mul_f32 v[196:197], v[94:95], v[90:91]
	v_pk_mul_f32 v[190:191], v[192:193], v[190:191]
	v_pk_mul_f32 v[194:195], v[196:197], v[194:195]
	v_cvt_pk_bf16_f32 v200, v190, v191
	v_cvt_pk_bf16_f32 v201, v194, v195
	ds_write_b16 v150, v200 offset:4608
	ds_write_b16_d16_hi v150, v200 offset:4752
	ds_write_b16 v150, v201 offset:4896
	ds_write_b16_d16_hi v150, v201 offset:5040
	v_pk_mul_f32 v[190:191], v[84:85], v[84:85]
	v_pk_mul_f32 v[194:195], v[86:87], v[86:87]
	v_pk_fma_f32 v[190:191], v[190:191], v[184:185], v[182:183]
	v_pk_fma_f32 v[194:195], v[194:195], v[184:185], v[182:183]
	v_pk_mul_f32 v[190:191], v[84:85], v[190:191]
	v_pk_mul_f32 v[194:195], v[86:87], v[194:195]
	v_pk_mul_f32 v[192:193], v[80:81], v[186:187]
	v_pk_mul_f32 v[196:197], v[82:83], v[186:187]
	v_exp_f32_e32 v190, v190
	v_exp_f32_e32 v191, v191
	v_exp_f32_e32 v192, v192
	v_exp_f32_e32 v193, v193
	v_exp_f32_e32 v194, v194
	v_exp_f32_e32 v195, v195
	v_exp_f32_e32 v196, v196
	v_exp_f32_e32 v197, v197
	v_pk_add_f32 v[190:191], v[190:191], v[188:189]
	v_pk_add_f32 v[192:193], v[192:193], v[188:189]
	v_pk_add_f32 v[194:195], v[194:195], v[188:189]
	v_pk_add_f32 v[196:197], v[196:197], v[188:189]
	v_pk_mul_f32 v[190:191], v[190:191], v[192:193]
	v_pk_mul_f32 v[194:195], v[194:195], v[196:197]
	v_rcp_f32_e32 v190, v190
	v_rcp_f32_e32 v191, v191
	v_rcp_f32_e32 v194, v194
	v_rcp_f32_e32 v195, v195
	v_pk_mul_f32 v[192:193], v[84:85], v[80:81]
	v_pk_mul_f32 v[196:197], v[86:87], v[82:83]
	v_pk_mul_f32 v[190:191], v[192:193], v[190:191]
	v_pk_mul_f32 v[194:195], v[196:197], v[194:195]
	v_cvt_pk_bf16_f32 v200, v190, v191
	v_cvt_pk_bf16_f32 v201, v194, v195
	ds_write_b16 v150, v200 offset:4640
	ds_write_b16_d16_hi v150, v200 offset:4784
	ds_write_b16 v150, v201 offset:4928
	ds_write_b16_d16_hi v150, v201 offset:5072
	v_pk_mul_f32 v[190:191], v[76:77], v[76:77]
	v_pk_mul_f32 v[194:195], v[78:79], v[78:79]
	v_pk_fma_f32 v[190:191], v[190:191], v[184:185], v[182:183]
	v_pk_fma_f32 v[194:195], v[194:195], v[184:185], v[182:183]
	v_pk_mul_f32 v[190:191], v[76:77], v[190:191]
	v_pk_mul_f32 v[194:195], v[78:79], v[194:195]
	v_pk_mul_f32 v[192:193], v[72:73], v[186:187]
	v_pk_mul_f32 v[196:197], v[74:75], v[186:187]
	v_exp_f32_e32 v190, v190
	v_exp_f32_e32 v191, v191
	v_exp_f32_e32 v192, v192
	v_exp_f32_e32 v193, v193
	v_exp_f32_e32 v194, v194
	v_exp_f32_e32 v195, v195
	v_exp_f32_e32 v196, v196
	v_exp_f32_e32 v197, v197
	v_pk_add_f32 v[190:191], v[190:191], v[188:189]
	v_pk_add_f32 v[192:193], v[192:193], v[188:189]
	v_pk_add_f32 v[194:195], v[194:195], v[188:189]
	v_pk_add_f32 v[196:197], v[196:197], v[188:189]
	v_pk_mul_f32 v[190:191], v[190:191], v[192:193]
	v_pk_mul_f32 v[194:195], v[194:195], v[196:197]
	v_rcp_f32_e32 v190, v190
	v_rcp_f32_e32 v191, v191
	v_rcp_f32_e32 v194, v194
	v_rcp_f32_e32 v195, v195
	v_pk_mul_f32 v[192:193], v[76:77], v[72:73]
	v_pk_mul_f32 v[196:197], v[78:79], v[74:75]
	v_pk_mul_f32 v[190:191], v[192:193], v[190:191]
	v_pk_mul_f32 v[194:195], v[196:197], v[194:195]
	v_cvt_pk_bf16_f32 v200, v190, v191
	v_cvt_pk_bf16_f32 v201, v194, v195
	ds_write_b16 v150, v200 offset:6912
	ds_write_b16_d16_hi v150, v200 offset:7056
	ds_write_b16 v150, v201 offset:7200
	ds_write_b16_d16_hi v150, v201 offset:7344
	v_pk_mul_f32 v[190:191], v[68:69], v[68:69]
	v_pk_mul_f32 v[194:195], v[70:71], v[70:71]
	v_pk_fma_f32 v[190:191], v[190:191], v[184:185], v[182:183]
	v_pk_fma_f32 v[194:195], v[194:195], v[184:185], v[182:183]
	v_pk_mul_f32 v[190:191], v[68:69], v[190:191]
	v_pk_mul_f32 v[194:195], v[70:71], v[194:195]
	v_pk_mul_f32 v[192:193], v[64:65], v[186:187]
	v_pk_mul_f32 v[196:197], v[66:67], v[186:187]
	v_exp_f32_e32 v190, v190
	v_exp_f32_e32 v191, v191
	v_exp_f32_e32 v192, v192
	v_exp_f32_e32 v193, v193
	v_exp_f32_e32 v194, v194
	v_exp_f32_e32 v195, v195
	v_exp_f32_e32 v196, v196
	v_exp_f32_e32 v197, v197
	v_pk_add_f32 v[190:191], v[190:191], v[188:189]
	v_pk_add_f32 v[192:193], v[192:193], v[188:189]
	v_pk_add_f32 v[194:195], v[194:195], v[188:189]
	v_pk_add_f32 v[196:197], v[196:197], v[188:189]
	v_pk_mul_f32 v[190:191], v[190:191], v[192:193]
	v_pk_mul_f32 v[194:195], v[194:195], v[196:197]
	v_rcp_f32_e32 v190, v190
	v_rcp_f32_e32 v191, v191
	v_rcp_f32_e32 v194, v194
	v_rcp_f32_e32 v195, v195
	v_pk_mul_f32 v[192:193], v[68:69], v[64:65]
	v_pk_mul_f32 v[196:197], v[70:71], v[66:67]
	v_pk_mul_f32 v[190:191], v[192:193], v[190:191]
	v_pk_mul_f32 v[194:195], v[196:197], v[194:195]
	v_cvt_pk_bf16_f32 v200, v190, v191
	v_cvt_pk_bf16_f32 v201, v194, v195
	ds_write_b16 v150, v200 offset:6944
	ds_write_b16_d16_hi v150, v200 offset:7088
	ds_write_b16 v150, v201 offset:7232
	ds_write_b16_d16_hi v150, v201 offset:7376
	v_pk_mul_f32 v[190:191], v[60:61], v[60:61]
	v_pk_mul_f32 v[194:195], v[62:63], v[62:63]
	v_pk_fma_f32 v[190:191], v[190:191], v[184:185], v[182:183]
	v_pk_fma_f32 v[194:195], v[194:195], v[184:185], v[182:183]
	v_pk_mul_f32 v[190:191], v[60:61], v[190:191]
	v_pk_mul_f32 v[194:195], v[62:63], v[194:195]
	v_pk_mul_f32 v[192:193], v[56:57], v[186:187]
	v_pk_mul_f32 v[196:197], v[58:59], v[186:187]
	v_exp_f32_e32 v190, v190
	v_exp_f32_e32 v191, v191
	v_exp_f32_e32 v192, v192
	v_exp_f32_e32 v193, v193
	v_exp_f32_e32 v194, v194
	v_exp_f32_e32 v195, v195
	v_exp_f32_e32 v196, v196
	v_exp_f32_e32 v197, v197
	v_pk_add_f32 v[190:191], v[190:191], v[188:189]
	v_pk_add_f32 v[192:193], v[192:193], v[188:189]
	v_pk_add_f32 v[194:195], v[194:195], v[188:189]
	v_pk_add_f32 v[196:197], v[196:197], v[188:189]
	v_pk_mul_f32 v[190:191], v[190:191], v[192:193]
	v_pk_mul_f32 v[194:195], v[194:195], v[196:197]
	v_rcp_f32_e32 v190, v190
	v_rcp_f32_e32 v191, v191
	v_rcp_f32_e32 v194, v194
	v_rcp_f32_e32 v195, v195
	v_pk_mul_f32 v[192:193], v[60:61], v[56:57]
	v_pk_mul_f32 v[196:197], v[62:63], v[58:59]
	v_pk_mul_f32 v[190:191], v[192:193], v[190:191]
	v_pk_mul_f32 v[194:195], v[196:197], v[194:195]
	v_cvt_pk_bf16_f32 v200, v190, v191
	v_cvt_pk_bf16_f32 v201, v194, v195
	ds_write_b16 v150, v200 offset:9216
	ds_write_b16_d16_hi v150, v200 offset:9360
	ds_write_b16 v150, v201 offset:9504
	ds_write_b16_d16_hi v150, v201 offset:9648
	v_pk_mul_f32 v[190:191], v[52:53], v[52:53]
	v_pk_mul_f32 v[194:195], v[54:55], v[54:55]
	v_pk_fma_f32 v[190:191], v[190:191], v[184:185], v[182:183]
	v_pk_fma_f32 v[194:195], v[194:195], v[184:185], v[182:183]
	v_pk_mul_f32 v[190:191], v[52:53], v[190:191]
	v_pk_mul_f32 v[194:195], v[54:55], v[194:195]
	v_pk_mul_f32 v[192:193], v[48:49], v[186:187]
	v_pk_mul_f32 v[196:197], v[50:51], v[186:187]
	v_exp_f32_e32 v190, v190
	v_exp_f32_e32 v191, v191
	v_exp_f32_e32 v192, v192
	v_exp_f32_e32 v193, v193
	v_exp_f32_e32 v194, v194
	v_exp_f32_e32 v195, v195
	v_exp_f32_e32 v196, v196
	v_exp_f32_e32 v197, v197
	v_pk_add_f32 v[190:191], v[190:191], v[188:189]
	v_pk_add_f32 v[192:193], v[192:193], v[188:189]
	v_pk_add_f32 v[194:195], v[194:195], v[188:189]
	v_pk_add_f32 v[196:197], v[196:197], v[188:189]
	v_pk_mul_f32 v[190:191], v[190:191], v[192:193]
	v_pk_mul_f32 v[194:195], v[194:195], v[196:197]
	v_rcp_f32_e32 v190, v190
	v_rcp_f32_e32 v191, v191
	v_rcp_f32_e32 v194, v194
	v_rcp_f32_e32 v195, v195
	v_pk_mul_f32 v[192:193], v[52:53], v[48:49]
	v_pk_mul_f32 v[196:197], v[54:55], v[50:51]
	v_pk_mul_f32 v[190:191], v[192:193], v[190:191]
	v_pk_mul_f32 v[194:195], v[196:197], v[194:195]
	v_cvt_pk_bf16_f32 v200, v190, v191
	v_cvt_pk_bf16_f32 v201, v194, v195
	ds_write_b16 v150, v200 offset:9248
	ds_write_b16_d16_hi v150, v200 offset:9392
	ds_write_b16 v150, v201 offset:9536
	ds_write_b16_d16_hi v150, v201 offset:9680
	v_pk_mul_f32 v[190:191], v[44:45], v[44:45]
	v_pk_mul_f32 v[194:195], v[46:47], v[46:47]
	v_pk_fma_f32 v[190:191], v[190:191], v[184:185], v[182:183]
	v_pk_fma_f32 v[194:195], v[194:195], v[184:185], v[182:183]
	v_pk_mul_f32 v[190:191], v[44:45], v[190:191]
	v_pk_mul_f32 v[194:195], v[46:47], v[194:195]
	v_pk_mul_f32 v[192:193], v[40:41], v[186:187]
	v_pk_mul_f32 v[196:197], v[42:43], v[186:187]
	v_exp_f32_e32 v190, v190
	v_exp_f32_e32 v191, v191
	v_exp_f32_e32 v192, v192
	v_exp_f32_e32 v193, v193
	v_exp_f32_e32 v194, v194
	v_exp_f32_e32 v195, v195
	v_exp_f32_e32 v196, v196
	v_exp_f32_e32 v197, v197
	v_pk_add_f32 v[190:191], v[190:191], v[188:189]
	v_pk_add_f32 v[192:193], v[192:193], v[188:189]
	v_pk_add_f32 v[194:195], v[194:195], v[188:189]
	v_pk_add_f32 v[196:197], v[196:197], v[188:189]
	v_pk_mul_f32 v[190:191], v[190:191], v[192:193]
	v_pk_mul_f32 v[194:195], v[194:195], v[196:197]
	v_rcp_f32_e32 v190, v190
	v_rcp_f32_e32 v191, v191
	v_rcp_f32_e32 v194, v194
	v_rcp_f32_e32 v195, v195
	v_pk_mul_f32 v[192:193], v[44:45], v[40:41]
	v_pk_mul_f32 v[196:197], v[46:47], v[42:43]
	v_pk_mul_f32 v[190:191], v[192:193], v[190:191]
	v_pk_mul_f32 v[194:195], v[196:197], v[194:195]
	v_cvt_pk_bf16_f32 v200, v190, v191
	v_cvt_pk_bf16_f32 v201, v194, v195
	ds_write_b16 v150, v200 offset:11520
	ds_write_b16_d16_hi v150, v200 offset:11664
	ds_write_b16 v150, v201 offset:11808
	ds_write_b16_d16_hi v150, v201 offset:11952
	v_pk_mul_f32 v[190:191], v[36:37], v[36:37]
	v_pk_mul_f32 v[194:195], v[38:39], v[38:39]
	v_pk_fma_f32 v[190:191], v[190:191], v[184:185], v[182:183]
	v_pk_fma_f32 v[194:195], v[194:195], v[184:185], v[182:183]
	v_pk_mul_f32 v[190:191], v[36:37], v[190:191]
	v_pk_mul_f32 v[194:195], v[38:39], v[194:195]
	v_pk_mul_f32 v[192:193], v[32:33], v[186:187]
	v_pk_mul_f32 v[196:197], v[34:35], v[186:187]
	v_exp_f32_e32 v190, v190
	v_exp_f32_e32 v191, v191
	v_exp_f32_e32 v192, v192
	v_exp_f32_e32 v193, v193
	v_exp_f32_e32 v194, v194
	v_exp_f32_e32 v195, v195
	v_exp_f32_e32 v196, v196
	v_exp_f32_e32 v197, v197
	v_pk_add_f32 v[190:191], v[190:191], v[188:189]
	v_pk_add_f32 v[192:193], v[192:193], v[188:189]
	v_pk_add_f32 v[194:195], v[194:195], v[188:189]
	v_pk_add_f32 v[196:197], v[196:197], v[188:189]
	v_pk_mul_f32 v[190:191], v[190:191], v[192:193]
	v_pk_mul_f32 v[194:195], v[194:195], v[196:197]
	v_rcp_f32_e32 v190, v190
	v_rcp_f32_e32 v191, v191
	v_rcp_f32_e32 v194, v194
	v_rcp_f32_e32 v195, v195
	v_pk_mul_f32 v[192:193], v[36:37], v[32:33]
	v_pk_mul_f32 v[196:197], v[38:39], v[34:35]
	v_pk_mul_f32 v[190:191], v[192:193], v[190:191]
	v_pk_mul_f32 v[194:195], v[196:197], v[194:195]
	v_cvt_pk_bf16_f32 v200, v190, v191
	v_cvt_pk_bf16_f32 v201, v194, v195
	ds_write_b16 v150, v200 offset:11552
	ds_write_b16_d16_hi v150, v200 offset:11696
	ds_write_b16 v150, v201 offset:11840
	ds_write_b16_d16_hi v150, v201 offset:11984
	v_pk_mul_f32 v[190:191], v[28:29], v[28:29]
	v_pk_mul_f32 v[194:195], v[30:31], v[30:31]
	v_pk_fma_f32 v[190:191], v[190:191], v[184:185], v[182:183]
	v_pk_fma_f32 v[194:195], v[194:195], v[184:185], v[182:183]
	v_pk_mul_f32 v[190:191], v[28:29], v[190:191]
	v_pk_mul_f32 v[194:195], v[30:31], v[194:195]
	v_pk_mul_f32 v[192:193], v[24:25], v[186:187]
	v_pk_mul_f32 v[196:197], v[26:27], v[186:187]
	v_exp_f32_e32 v190, v190
	v_exp_f32_e32 v191, v191
	v_exp_f32_e32 v192, v192
	v_exp_f32_e32 v193, v193
	v_exp_f32_e32 v194, v194
	v_exp_f32_e32 v195, v195
	v_exp_f32_e32 v196, v196
	v_exp_f32_e32 v197, v197
	v_pk_add_f32 v[190:191], v[190:191], v[188:189]
	v_pk_add_f32 v[192:193], v[192:193], v[188:189]
	v_pk_add_f32 v[194:195], v[194:195], v[188:189]
	v_pk_add_f32 v[196:197], v[196:197], v[188:189]
	v_pk_mul_f32 v[190:191], v[190:191], v[192:193]
	v_pk_mul_f32 v[194:195], v[194:195], v[196:197]
	v_rcp_f32_e32 v190, v190
	v_rcp_f32_e32 v191, v191
	v_rcp_f32_e32 v194, v194
	v_rcp_f32_e32 v195, v195
	v_pk_mul_f32 v[192:193], v[28:29], v[24:25]
	v_pk_mul_f32 v[196:197], v[30:31], v[26:27]
	v_pk_mul_f32 v[190:191], v[192:193], v[190:191]
	v_pk_mul_f32 v[194:195], v[196:197], v[194:195]
	v_cvt_pk_bf16_f32 v200, v190, v191
	v_cvt_pk_bf16_f32 v201, v194, v195
	ds_write_b16 v150, v200 offset:13824
	ds_write_b16_d16_hi v150, v200 offset:13968
	ds_write_b16 v150, v201 offset:14112
	ds_write_b16_d16_hi v150, v201 offset:14256
	v_pk_mul_f32 v[190:191], v[16:17], v[16:17]
	v_pk_mul_f32 v[194:195], v[18:19], v[18:19]
	v_pk_fma_f32 v[190:191], v[190:191], v[184:185], v[182:183]
	v_pk_fma_f32 v[194:195], v[194:195], v[184:185], v[182:183]
	v_pk_mul_f32 v[190:191], v[16:17], v[190:191]
	v_pk_mul_f32 v[194:195], v[18:19], v[194:195]
	v_pk_mul_f32 v[192:193], v[12:13], v[186:187]
	v_pk_mul_f32 v[196:197], v[14:15], v[186:187]
	v_exp_f32_e32 v190, v190
	v_exp_f32_e32 v191, v191
	v_exp_f32_e32 v192, v192
	v_exp_f32_e32 v193, v193
	v_exp_f32_e32 v194, v194
	v_exp_f32_e32 v195, v195
	v_exp_f32_e32 v196, v196
	v_exp_f32_e32 v197, v197
	v_pk_add_f32 v[190:191], v[190:191], v[188:189]
	v_pk_add_f32 v[192:193], v[192:193], v[188:189]
	v_pk_add_f32 v[194:195], v[194:195], v[188:189]
	v_pk_add_f32 v[196:197], v[196:197], v[188:189]
	v_pk_mul_f32 v[190:191], v[190:191], v[192:193]
	v_pk_mul_f32 v[194:195], v[194:195], v[196:197]
	v_rcp_f32_e32 v190, v190
	v_rcp_f32_e32 v191, v191
	v_rcp_f32_e32 v194, v194
	v_rcp_f32_e32 v195, v195
	v_pk_mul_f32 v[192:193], v[16:17], v[12:13]
	v_pk_mul_f32 v[196:197], v[18:19], v[14:15]
	v_pk_mul_f32 v[190:191], v[192:193], v[190:191]
	v_pk_mul_f32 v[194:195], v[196:197], v[194:195]
	v_cvt_pk_bf16_f32 v200, v190, v191
	v_cvt_pk_bf16_f32 v201, v194, v195
	ds_write_b16 v150, v200 offset:13856
	ds_write_b16_d16_hi v150, v200 offset:14000
	ds_write_b16 v150, v201 offset:14144
	ds_write_b16_d16_hi v150, v201 offset:14288
	v_pk_mul_f32 v[190:191], v[4:5], v[4:5]
	v_pk_mul_f32 v[194:195], v[6:7], v[6:7]
	v_pk_fma_f32 v[190:191], v[190:191], v[184:185], v[182:183]
	v_pk_fma_f32 v[194:195], v[194:195], v[184:185], v[182:183]
	v_pk_mul_f32 v[190:191], v[4:5], v[190:191]
	v_pk_mul_f32 v[194:195], v[6:7], v[194:195]
	v_pk_mul_f32 v[192:193], v[20:21], v[186:187]
	v_pk_mul_f32 v[196:197], v[22:23], v[186:187]
	v_exp_f32_e32 v190, v190
	v_exp_f32_e32 v191, v191
	v_exp_f32_e32 v192, v192
	v_exp_f32_e32 v193, v193
	v_exp_f32_e32 v194, v194
	v_exp_f32_e32 v195, v195
	v_exp_f32_e32 v196, v196
	v_exp_f32_e32 v197, v197
	v_pk_add_f32 v[190:191], v[190:191], v[188:189]
	v_pk_add_f32 v[192:193], v[192:193], v[188:189]
	v_pk_add_f32 v[194:195], v[194:195], v[188:189]
	v_pk_add_f32 v[196:197], v[196:197], v[188:189]
	v_pk_mul_f32 v[190:191], v[190:191], v[192:193]
	v_pk_mul_f32 v[194:195], v[194:195], v[196:197]
	v_rcp_f32_e32 v190, v190
	v_rcp_f32_e32 v191, v191
	v_rcp_f32_e32 v194, v194
	v_rcp_f32_e32 v195, v195
	v_pk_mul_f32 v[192:193], v[4:5], v[20:21]
	v_pk_mul_f32 v[196:197], v[6:7], v[22:23]
	v_pk_mul_f32 v[190:191], v[192:193], v[190:191]
	v_pk_mul_f32 v[194:195], v[196:197], v[194:195]
	v_cvt_pk_bf16_f32 v200, v190, v191
	v_cvt_pk_bf16_f32 v201, v194, v195
	ds_write_b16 v150, v200 offset:16128
	ds_write_b16_d16_hi v150, v200 offset:16272
	ds_write_b16 v150, v201 offset:16416
	ds_write_b16_d16_hi v150, v201 offset:16560
	v_pk_mul_f32 v[190:191], v[0:1], v[0:1]
	v_pk_mul_f32 v[194:195], v[2:3], v[2:3]
	v_pk_fma_f32 v[190:191], v[190:191], v[184:185], v[182:183]
	v_pk_fma_f32 v[194:195], v[194:195], v[184:185], v[182:183]
	v_pk_mul_f32 v[190:191], v[0:1], v[190:191]
	v_pk_mul_f32 v[194:195], v[2:3], v[194:195]
	v_pk_mul_f32 v[192:193], v[8:9], v[186:187]
	v_pk_mul_f32 v[196:197], v[10:11], v[186:187]
	v_exp_f32_e32 v190, v190
	v_exp_f32_e32 v191, v191
	v_exp_f32_e32 v192, v192
	v_exp_f32_e32 v193, v193
	v_exp_f32_e32 v194, v194
	v_exp_f32_e32 v195, v195
	v_exp_f32_e32 v196, v196
	v_exp_f32_e32 v197, v197
	v_pk_add_f32 v[190:191], v[190:191], v[188:189]
	v_pk_add_f32 v[192:193], v[192:193], v[188:189]
	v_pk_add_f32 v[194:195], v[194:195], v[188:189]
	v_pk_add_f32 v[196:197], v[196:197], v[188:189]
	v_pk_mul_f32 v[190:191], v[190:191], v[192:193]
	v_pk_mul_f32 v[194:195], v[194:195], v[196:197]
	v_rcp_f32_e32 v190, v190
	v_rcp_f32_e32 v191, v191
	v_rcp_f32_e32 v194, v194
	v_rcp_f32_e32 v195, v195
	v_pk_mul_f32 v[192:193], v[0:1], v[8:9]
	v_pk_mul_f32 v[196:197], v[2:3], v[10:11]
	v_pk_mul_f32 v[190:191], v[192:193], v[190:191]
	v_pk_mul_f32 v[194:195], v[196:197], v[194:195]
	v_cvt_pk_bf16_f32 v200, v190, v191
	v_cvt_pk_bf16_f32 v201, v194, v195
	ds_write_b16 v150, v200 offset:16160
	ds_write_b16_d16_hi v150, v200 offset:16304
	ds_write_b16 v150, v201 offset:16448
	ds_write_b16_d16_hi v150, v201 offset:16592
	s_lshl_b32 s20, s51, 2
	s_lshl_b32 s44, s52, 2
	s_and_b32 s20, s20, 0x7fffff0
	v_add_u32_e32 v134, s46, v149
	s_or_b32 s20, s44, s20
	v_ashrrev_i32_e32 v135, 31, v134
	v_lshlrev_b64 v[134:135], 12, v[134:135]
	s_mov_b64 s[44:45], 0
	v_add_lshl_u32 v0, s20, v147, 5
	s_waitcnt lgkmcnt(0)
	v_ashrrev_i32_e32 v1, 31, v0
	v_lshl_add_u64 v[0:1], v[0:1], 1, v[134:135]
	v_lshl_add_u64 v[0:1], v[132:133], 0, v[0:1]
	v_mov_b32_e32 v2, v153
